# P2a S3 epilogue rewritten: one wave-uniform branch instead of two per register, decay factors with packed ops inside the K loop, packed products, single bf16 pack + d16_hi store
# speedup vs baseline: 1.0073x; 1.0073x over previous
; #define LAS __attribute__((address_space(3)))
; #define MFMA32(a, b, c) __builtin_amdgcn_mfma_f32_32x32x16_bf16((a), (b), (c), 0, 0, 0)
; __device__ __forceinline__ void gdn_prep_phase(LAS unsigned char* lds, const GdnPrepArgs& A, int bid, int G, const unsigned char* zero_page) {
;     ...
;         const LAS unsigned char* ia = lds + (which ? L_QN : L_KN) + (32 * rt + r) * QS_ + 16 * hh;
;         const LAS unsigned char* ib = lds + L_KN + (32 * ct + r) * QS_ + 16 * hh;
;         f32x16 acc = zero16();
; #pragma unroll
;         for (int ks = 0; ks < 8; ++ks) acc = MFMA32(*(const LAS bf16x8*)(ia + 32 * ks), *(const LAS bf16x8*)(ib + 32 * ks), acc);
;         const LAS float* sc = (const LAS float*)(lds + L_SC);
;         const int j = 32 * ct + r; const float gfj = sc[j], gbj = sc[64 + j];
; #pragma unroll
;         for (int reg = 0; reg < 16; ++reg) {
;             const int i = 32 * rt + (reg & 3) + 8 * (reg >> 2) + 4 * hh; const float val = acc[reg];
;             const float ef = __expf(sc[i] - gfj), eb = __expf(sc[64 + i] - gbj);
.LBB0_209:
	s_mov_b32 s98, 0x3fb8aa3b
	ds_read2st64_b32 v[216:217], v55 offset1:1
	ds_read2st64_b32 v[136:137], v72 offset1:1
	ds_read2st64_b32 v[138:139], v74 offset1:1
	ds_read2st64_b32 v[140:141], v76 offset1:1
	ds_read2st64_b32 v[142:143], v78 offset1:1
	ds_read2st64_b32 v[144:145], v80 offset1:1
	ds_read2st64_b32 v[146:147], v82 offset1:1
	ds_read2st64_b32 v[148:149], v84 offset1:1
	ds_read2st64_b32 v[150:151], v86 offset1:1
	ds_read2st64_b32 v[152:153], v88 offset1:1
	ds_read2st64_b32 v[154:155], v90 offset1:1
	ds_read2st64_b32 v[156:157], v92 offset1:1
	ds_read2st64_b32 v[158:159], v94 offset1:1
	ds_read2st64_b32 v[160:161], v96 offset1:1
	ds_read2st64_b32 v[162:163], v98 offset1:1
	ds_read2st64_b32 v[174:175], v100 offset1:1
	ds_read2st64_b32 v[176:177], v102 offset1:1
	ds_read2st64_b32 v[178:179], v72 offset0:2 offset1:3
	ds_read2st64_b32 v[180:181], v74 offset0:2 offset1:3
	ds_read2st64_b32 v[182:183], v76 offset0:2 offset1:3
	ds_read2st64_b32 v[230:231], v78 offset0:2 offset1:3
	ds_read2st64_b32 v[232:233], v80 offset0:2 offset1:3
	ds_read2st64_b32 v[234:235], v82 offset0:2 offset1:3
	ds_read2st64_b32 v[236:237], v84 offset0:2 offset1:3
	ds_read2st64_b32 v[238:239], v86 offset0:2 offset1:3
	ds_read2st64_b32 v[240:241], v88 offset0:2 offset1:3
	ds_read2st64_b32 v[242:243], v90 offset0:2 offset1:3
	ds_read2st64_b32 v[244:245], v92 offset0:2 offset1:3
	ds_read2st64_b32 v[248:249], v94 offset0:2 offset1:3
	ds_read2st64_b32 v[208:209], v96 offset0:2 offset1:3
	ds_read2st64_b32 v[210:211], v98 offset0:2 offset1:3
	ds_read2st64_b32 v[212:213], v100 offset0:2 offset1:3
	ds_read2st64_b32 v[214:215], v102 offset0:2 offset1:3
	ds_read_b128 v[32:35], v190
	ds_read_b128 v[36:39], v191
	s_waitcnt lgkmcnt(0)
	v_mfma_f32_32x32x16_bf16 v[2:17], v[32:35], v[36:39], 0
	v_pk_add_f32 v[136:137], v[136:137], v[216:217] neg_lo:[0,1] neg_hi:[0,1]
	v_pk_add_f32 v[138:139], v[138:139], v[216:217] neg_lo:[0,1] neg_hi:[0,1]
	v_pk_mul_f32 v[136:137], v[136:137], s[98:99] op_sel_hi:[1,0]
	v_pk_mul_f32 v[138:139], v[138:139], s[98:99] op_sel_hi:[1,0]
	v_exp_f32_e32 v136, v136
	v_exp_f32_e32 v137, v137
	v_exp_f32_e32 v138, v138
	v_exp_f32_e32 v139, v139
	ds_read_b128 v[32:35], v190 offset:32
	ds_read_b128 v[36:39], v191 offset:32
	s_waitcnt lgkmcnt(0)
	v_mfma_f32_32x32x16_bf16 v[2:17], v[32:35], v[36:39], v[2:17]
	v_pk_add_f32 v[140:141], v[140:141], v[216:217] neg_lo:[0,1] neg_hi:[0,1]
	v_pk_add_f32 v[142:143], v[142:143], v[216:217] neg_lo:[0,1] neg_hi:[0,1]
	v_pk_mul_f32 v[140:141], v[140:141], s[98:99] op_sel_hi:[1,0]
	v_pk_mul_f32 v[142:143], v[142:143], s[98:99] op_sel_hi:[1,0]
	v_exp_f32_e32 v140, v140
	v_exp_f32_e32 v141, v141
	v_exp_f32_e32 v142, v142
	v_exp_f32_e32 v143, v143
	ds_read_b128 v[32:35], v190 offset:64
	ds_read_b128 v[36:39], v191 offset:64
	s_waitcnt lgkmcnt(0)
	v_mfma_f32_32x32x16_bf16 v[2:17], v[32:35], v[36:39], v[2:17]
	v_pk_add_f32 v[144:145], v[144:145], v[216:217] neg_lo:[0,1] neg_hi:[0,1]
	v_pk_add_f32 v[146:147], v[146:147], v[216:217] neg_lo:[0,1] neg_hi:[0,1]
	v_pk_mul_f32 v[144:145], v[144:145], s[98:99] op_sel_hi:[1,0]
	v_pk_mul_f32 v[146:147], v[146:147], s[98:99] op_sel_hi:[1,0]
	v_exp_f32_e32 v144, v144
	v_exp_f32_e32 v145, v145
	v_exp_f32_e32 v146, v146
	v_exp_f32_e32 v147, v147
	ds_read_b128 v[32:35], v190 offset:96
	ds_read_b128 v[36:39], v191 offset:96
	s_waitcnt lgkmcnt(0)
	v_mfma_f32_32x32x16_bf16 v[2:17], v[32:35], v[36:39], v[2:17]
	v_pk_add_f32 v[148:149], v[148:149], v[216:217] neg_lo:[0,1] neg_hi:[0,1]
	v_pk_add_f32 v[150:151], v[150:151], v[216:217] neg_lo:[0,1] neg_hi:[0,1]
	v_pk_mul_f32 v[148:149], v[148:149], s[98:99] op_sel_hi:[1,0]
	v_pk_mul_f32 v[150:151], v[150:151], s[98:99] op_sel_hi:[1,0]
	v_exp_f32_e32 v148, v148
	v_exp_f32_e32 v149, v149
	v_exp_f32_e32 v150, v150
	v_exp_f32_e32 v151, v151
	ds_read_b128 v[32:35], v190 offset:128
	ds_read_b128 v[36:39], v191 offset:128
	s_waitcnt lgkmcnt(0)
	v_mfma_f32_32x32x16_bf16 v[2:17], v[32:35], v[36:39], v[2:17]
	v_pk_add_f32 v[152:153], v[152:153], v[216:217] neg_lo:[0,1] neg_hi:[0,1]
	v_pk_add_f32 v[154:155], v[154:155], v[216:217] neg_lo:[0,1] neg_hi:[0,1]
	v_pk_mul_f32 v[152:153], v[152:153], s[98:99] op_sel_hi:[1,0]
	v_pk_mul_f32 v[154:155], v[154:155], s[98:99] op_sel_hi:[1,0]
	v_exp_f32_e32 v152, v152
	v_exp_f32_e32 v153, v153
	v_exp_f32_e32 v154, v154
	v_exp_f32_e32 v155, v155
	ds_read_b128 v[32:35], v190 offset:160
	ds_read_b128 v[36:39], v191 offset:160
	s_waitcnt lgkmcnt(0)
	v_mfma_f32_32x32x16_bf16 v[2:17], v[32:35], v[36:39], v[2:17]
	v_pk_add_f32 v[156:157], v[156:157], v[216:217] neg_lo:[0,1] neg_hi:[0,1]
	v_pk_add_f32 v[158:159], v[158:159], v[216:217] neg_lo:[0,1] neg_hi:[0,1]
	v_pk_mul_f32 v[156:157], v[156:157], s[98:99] op_sel_hi:[1,0]
	v_pk_mul_f32 v[158:159], v[158:159], s[98:99] op_sel_hi:[1,0]
	v_exp_f32_e32 v156, v156
	v_exp_f32_e32 v157, v157
	v_exp_f32_e32 v158, v158
	v_exp_f32_e32 v159, v159
	ds_read_b128 v[32:35], v190 offset:192
	ds_read_b128 v[36:39], v191 offset:192
	s_waitcnt lgkmcnt(0)
	v_mfma_f32_32x32x16_bf16 v[2:17], v[32:35], v[36:39], v[2:17]
	v_pk_add_f32 v[160:161], v[160:161], v[216:217] neg_lo:[0,1] neg_hi:[0,1]
	v_pk_add_f32 v[162:163], v[162:163], v[216:217] neg_lo:[0,1] neg_hi:[0,1]
	v_pk_mul_f32 v[160:161], v[160:161], s[98:99] op_sel_hi:[1,0]
	v_pk_mul_f32 v[162:163], v[162:163], s[98:99] op_sel_hi:[1,0]
	v_exp_f32_e32 v160, v160
	v_exp_f32_e32 v161, v161
	v_exp_f32_e32 v162, v162
	v_exp_f32_e32 v163, v163
	ds_read_b128 v[32:35], v190 offset:224
	ds_read_b128 v[36:39], v191 offset:224
	s_waitcnt lgkmcnt(0)
	v_mfma_f32_32x32x16_bf16 v[2:17], v[32:35], v[36:39], v[2:17]
	v_pk_add_f32 v[174:175], v[174:175], v[216:217] neg_lo:[0,1] neg_hi:[0,1]
	v_pk_add_f32 v[176:177], v[176:177], v[216:217] neg_lo:[0,1] neg_hi:[0,1]
	v_pk_mul_f32 v[174:175], v[174:175], s[98:99] op_sel_hi:[1,0]
	v_pk_mul_f32 v[176:177], v[176:177], s[98:99] op_sel_hi:[1,0]
	v_exp_f32_e32 v174, v174
	v_exp_f32_e32 v175, v175
	v_exp_f32_e32 v176, v176
	v_exp_f32_e32 v177, v177
	s_nop 3
	s_nop 0
	s_and_b64 vcc, exec, s[4:5]
	s_cbranch_vccz .Ls3_lpath
; #define LAS __attribute__((address_space(3)))
; __device__ __forceinline__ unsigned pkbf(float a, float b) { bf16x2_t v = __builtin_convertvector((f32x2_t){a, b}, bf16x2_t); return __builtin_bit_cast(unsigned, v); }
; __device__ __forceinline__ void gdn_prep_phase(LAS unsigned char* lds, const GdnPrepArgs& A, int bid, int G, const unsigned char* zero_page) {
;     ...
;             const int i = 32 * rt + (reg & 3) + 8 * (reg >> 2) + 4 * hh; const float val = acc[reg];
;             const float ef = __expf(sc[i] - gfj), eb = __expf(sc[64 + i] - gbj);
;             if (which == 0) {
;                 const float lf = (i > j) ? sc[128 + i] * val * ef : 0.f, lb = (i < j) ? sc[192 + i] * val * eb : 0.f;
;                 ((LAS float*)(lds + L_LPF))[i * 64 + (j & 3) * 16 + (j >> 2)] = lf;
;                 const int i2 = 63 - i, j2 = 63 - j;
;                 ((LAS float*)(lds + L_LPB))[i2 * 64 + (j2 & 3) * 16 + (j2 >> 2)] = lb;
;             } else {
;                 const float af = (i >= j) ? QSCALE * val * ef : 0.f, ab = (i <= j) ? QSCALE * val * eb : 0.f;
;                 *(LAS unsigned short*)(lds + L_AF + i * AS_ + j * 2) = (unsigned short)(pkbf(af, 0.f) & 0xffffu);
;                 *(LAS unsigned short*)(lds + L_AB + i * AS_ + j * 2) = (unsigned short)(pkbf(ab, 0.f) & 0xffffu);
	v_mul_f32_e32 v218, 0x3db504f3, v2
	v_pk_mul_f32 v[220:221], v[136:137], v[218:219] op_sel_hi:[1,0]
	s_nop 0
	v_cndmask_b32_e64 v220, v220, 0, s[6:7]
	v_readlane_b32 s48, v255, 15
	v_readlane_b32 s49, v255, 16
	s_nop 1
	v_cndmask_b32_e64 v221, v221, 0, s[48:49]
	v_cvt_pk_bf16_f32 v220, v220, v221
	ds_write_b16 v228, v220
	ds_write_b16_d16_hi v229, v220
	v_mul_f32_e32 v218, 0x3db504f3, v3
	v_pk_mul_f32 v[220:221], v[138:139], v[218:219] op_sel_hi:[1,0]
	v_readlane_b32 s46, v255, 17
	v_readlane_b32 s47, v255, 18
	s_nop 1
	v_cndmask_b32_e64 v220, v220, 0, s[46:47]
	v_cndmask_b32_e64 v221, 0, v221, s[6:7]
	v_cvt_pk_bf16_f32 v220, v220, v221
	ds_write_b16 v228, v220 offset:144
	ds_write_b16_d16_hi v229, v220 offset:144
	v_mul_f32_e32 v218, 0x3db504f3, v4
	v_pk_mul_f32 v[220:221], v[140:141], v[218:219] op_sel_hi:[1,0]
	v_readlane_b32 s46, v255, 19
	v_readlane_b32 s47, v255, 20
	s_nop 1
	v_cndmask_b32_e64 v220, v220, 0, s[46:47]
	v_readlane_b32 s48, v255, 21
	v_readlane_b32 s49, v255, 22
	s_nop 1
	v_cndmask_b32_e64 v221, v221, 0, s[48:49]
	v_cvt_pk_bf16_f32 v220, v220, v221
	ds_write_b16 v228, v220 offset:288
	ds_write_b16_d16_hi v229, v220 offset:288
	v_mul_f32_e32 v218, 0x3db504f3, v5
	v_pk_mul_f32 v[220:221], v[142:143], v[218:219] op_sel_hi:[1,0]
	v_readlane_b32 s46, v255, 23
	v_readlane_b32 s47, v255, 24
	s_nop 1
	v_cndmask_b32_e64 v220, v220, 0, s[46:47]
	v_readlane_b32 s48, v255, 25
	v_readlane_b32 s49, v255, 26
	s_nop 1
	v_cndmask_b32_e64 v221, v221, 0, s[48:49]
	v_cvt_pk_bf16_f32 v220, v220, v221
	ds_write_b16 v228, v220 offset:432
	ds_write_b16_d16_hi v229, v220 offset:432
	v_mul_f32_e32 v218, 0x3db504f3, v6
	v_pk_mul_f32 v[220:221], v[144:145], v[218:219] op_sel_hi:[1,0]
	v_readlane_b32 s46, v255, 27
	v_readlane_b32 s47, v255, 28
	s_nop 1
	v_cndmask_b32_e64 v220, v220, 0, s[46:47]
	v_readlane_b32 s48, v255, 29
	v_readlane_b32 s49, v255, 30
	s_nop 1
	v_cndmask_b32_e64 v221, v221, 0, s[48:49]
	v_cvt_pk_bf16_f32 v220, v220, v221
	ds_write_b16 v228, v220 offset:1152
	ds_write_b16_d16_hi v229, v220 offset:1152
	v_mul_f32_e32 v218, 0x3db504f3, v7
	v_pk_mul_f32 v[220:221], v[146:147], v[218:219] op_sel_hi:[1,0]
	v_readlane_b32 s46, v255, 31
	v_readlane_b32 s47, v255, 32
	s_nop 1
	v_cndmask_b32_e64 v220, v220, 0, s[46:47]
	v_readlane_b32 s48, v255, 33
	v_readlane_b32 s49, v255, 34
	s_nop 1
	v_cndmask_b32_e64 v221, v221, 0, s[48:49]
	v_cvt_pk_bf16_f32 v220, v220, v221
	ds_write_b16 v228, v220 offset:1296
	ds_write_b16_d16_hi v229, v220 offset:1296
	v_mul_f32_e32 v218, 0x3db504f3, v8
	v_pk_mul_f32 v[220:221], v[148:149], v[218:219] op_sel_hi:[1,0]
	v_readlane_b32 s46, v255, 35
	v_readlane_b32 s47, v255, 36
	s_nop 1
	v_cndmask_b32_e64 v220, v220, 0, s[46:47]
	v_readlane_b32 s48, v255, 37
	v_readlane_b32 s49, v255, 38
	s_nop 1
	v_cndmask_b32_e64 v221, v221, 0, s[48:49]
	v_cvt_pk_bf16_f32 v220, v220, v221
	ds_write_b16 v228, v220 offset:1440
	ds_write_b16_d16_hi v229, v220 offset:1440
	v_mul_f32_e32 v218, 0x3db504f3, v9
	v_pk_mul_f32 v[220:221], v[150:151], v[218:219] op_sel_hi:[1,0]
	v_readlane_b32 s46, v255, 39
	v_readlane_b32 s47, v255, 40
	s_nop 1
	v_cndmask_b32_e64 v220, v220, 0, s[46:47]
	v_readlane_b32 s48, v255, 41
	v_readlane_b32 s49, v255, 42
	s_nop 1
	v_cndmask_b32_e64 v221, v221, 0, s[48:49]
	v_cvt_pk_bf16_f32 v220, v220, v221
	ds_write_b16 v228, v220 offset:1584
	ds_write_b16_d16_hi v229, v220 offset:1584
	v_mul_f32_e32 v218, 0x3db504f3, v10
	v_pk_mul_f32 v[220:221], v[152:153], v[218:219] op_sel_hi:[1,0]
	v_readlane_b32 s46, v255, 43
	v_readlane_b32 s47, v255, 44
	s_nop 1
	v_cndmask_b32_e64 v220, v220, 0, s[46:47]
	v_readlane_b32 s48, v255, 45
	v_readlane_b32 s49, v255, 46
	s_nop 1
	v_cndmask_b32_e64 v221, v221, 0, s[48:49]
	v_cvt_pk_bf16_f32 v220, v220, v221
	ds_write_b16 v228, v220 offset:2304
	ds_write_b16_d16_hi v229, v220 offset:2304
	v_mul_f32_e32 v218, 0x3db504f3, v11
	v_pk_mul_f32 v[220:221], v[154:155], v[218:219] op_sel_hi:[1,0]
	s_nop 0
	v_cndmask_b32_e64 v220, v220, 0, s[74:75]
	v_cndmask_b32_e64 v221, v221, 0, s[76:77]
	v_cvt_pk_bf16_f32 v220, v220, v221
	ds_write_b16 v228, v220 offset:2448
	ds_write_b16_d16_hi v229, v220 offset:2448
	v_mul_f32_e32 v218, 0x3db504f3, v12
	v_pk_mul_f32 v[220:221], v[156:157], v[218:219] op_sel_hi:[1,0]
	s_nop 0
	v_cndmask_b32_e64 v220, v220, 0, s[58:59]
	v_cndmask_b32_e64 v221, v221, 0, s[60:61]
	v_cvt_pk_bf16_f32 v220, v220, v221
	ds_write_b16 v228, v220 offset:2592
	ds_write_b16_d16_hi v229, v220 offset:2592
	v_mul_f32_e32 v218, 0x3db504f3, v13
	v_pk_mul_f32 v[220:221], v[158:159], v[218:219] op_sel_hi:[1,0]
	s_nop 0
	v_cndmask_b32_e64 v220, v220, 0, s[62:63]
	v_cndmask_b32_e64 v221, v221, 0, s[64:65]
	v_cvt_pk_bf16_f32 v220, v220, v221
	ds_write_b16 v228, v220 offset:2736
	ds_write_b16_d16_hi v229, v220 offset:2736
	v_mul_f32_e32 v218, 0x3db504f3, v14
	v_pk_mul_f32 v[220:221], v[160:161], v[218:219] op_sel_hi:[1,0]
	s_nop 0
	v_cndmask_b32_e64 v220, v220, 0, s[84:85]
	v_cndmask_b32_e64 v221, v221, 0, s[78:79]
	v_cvt_pk_bf16_f32 v220, v220, v221
	ds_write_b16 v228, v220 offset:3456
	ds_write_b16_d16_hi v229, v220 offset:3456
	v_mul_f32_e32 v218, 0x3db504f3, v15
	v_pk_mul_f32 v[220:221], v[162:163], v[218:219] op_sel_hi:[1,0]
	s_nop 0
	v_cndmask_b32_e64 v220, v220, 0, s[80:81]
	v_cndmask_b32_e64 v221, v221, 0, s[26:27]
	v_cvt_pk_bf16_f32 v220, v220, v221
	ds_write_b16 v228, v220 offset:3600
	ds_write_b16_d16_hi v229, v220 offset:3600
	v_mul_f32_e32 v218, 0x3db504f3, v16
	v_pk_mul_f32 v[220:221], v[174:175], v[218:219] op_sel_hi:[1,0]
	s_nop 0
	v_cndmask_b32_e64 v220, v220, 0, s[28:29]
	v_cndmask_b32_e64 v221, v221, 0, s[30:31]
	v_cvt_pk_bf16_f32 v220, v220, v221
	ds_write_b16 v228, v220 offset:3744
	ds_write_b16_d16_hi v229, v220 offset:3744
	v_mul_f32_e32 v218, 0x3db504f3, v17
	v_pk_mul_f32 v[220:221], v[176:177], v[218:219] op_sel_hi:[1,0]
	s_nop 0
	v_cndmask_b32_e64 v220, v220, 0, s[24:25]
	v_cndmask_b32_e64 v221, v221, 0, s[36:37]
	v_cvt_pk_bf16_f32 v220, v220, v221
	ds_write_b16 v228, v220 offset:3888
	ds_write_b16_d16_hi v229, v220 offset:3888
	s_branch .Ls3_done
; #define LAS __attribute__((address_space(3)))
; __device__ __forceinline__ void gdn_prep_phase(LAS unsigned char* lds, const GdnPrepArgs& A, int bid, int G, const unsigned char* zero_page) {
;     ...
;             const int i = 32 * rt + (reg & 3) + 8 * (reg >> 2) + 4 * hh; const float val = acc[reg];
;             const float ef = __expf(sc[i] - gfj), eb = __expf(sc[64 + i] - gbj);
;             if (which == 0) {
;                 const float lf = (i > j) ? sc[128 + i] * val * ef : 0.f, lb = (i < j) ? sc[192 + i] * val * eb : 0.f;
;                 ((LAS float*)(lds + L_LPF))[i * 64 + (j & 3) * 16 + (j >> 2)] = lf;
;                 const int i2 = 63 - i, j2 = 63 - j;
;                 ((LAS float*)(lds + L_LPB))[i2 * 64 + (j2 & 3) * 16 + (j2 >> 2)] = lb;
.Ls3_lpath:
	v_pk_mul_f32 v[178:179], v[178:179], v[2:3] op_sel_hi:[1,0]
	s_nop 0
	v_pk_mul_f32 v[178:179], v[178:179], v[136:137]
	v_readlane_b32 s46, v255, 15
	v_readlane_b32 s47, v255, 16
	s_nop 1
	v_cndmask_b32_e64 v178, 0, v178, s[46:47]
	v_cndmask_b32_e64 v179, 0, v179, s[6:7]
	ds_write_b32 v192, v178
	ds_write_b32 v73, v179
	v_pk_mul_f32 v[180:181], v[180:181], v[2:3] op_sel:[0,1] op_sel_hi:[1,1]
	s_nop 0
	v_pk_mul_f32 v[180:181], v[180:181], v[138:139]
	v_readlane_b32 s46, v255, 13
	v_readlane_b32 s47, v255, 14
	s_nop 1
	v_cndmask_b32_e64 v180, 0, v180, s[46:47]
	v_readlane_b32 s48, v255, 17
	v_readlane_b32 s49, v255, 18
	s_nop 1
	v_cndmask_b32_e64 v181, 0, v181, s[48:49]
	ds_write_b32 v193, v180
	ds_write_b32 v75, v181
	v_pk_mul_f32 v[182:183], v[182:183], v[4:5] op_sel_hi:[1,0]
	s_nop 0
	v_pk_mul_f32 v[182:183], v[182:183], v[140:141]
	v_readlane_b32 s46, v255, 21
	v_readlane_b32 s47, v255, 22
	s_nop 1
	v_cndmask_b32_e64 v182, 0, v182, s[46:47]
	v_readlane_b32 s48, v255, 19
	v_readlane_b32 s49, v255, 20
	s_nop 1
	v_cndmask_b32_e64 v183, 0, v183, s[48:49]
	ds_write_b32 v194, v182
	ds_write_b32 v77, v183
	v_pk_mul_f32 v[230:231], v[230:231], v[4:5] op_sel:[0,1] op_sel_hi:[1,1]
	s_nop 0
	v_pk_mul_f32 v[230:231], v[230:231], v[142:143]
	v_readlane_b32 s46, v255, 25
	v_readlane_b32 s47, v255, 26
	s_nop 1
	v_cndmask_b32_e64 v230, 0, v230, s[46:47]
	v_readlane_b32 s48, v255, 23
	v_readlane_b32 s49, v255, 24
	s_nop 1
	v_cndmask_b32_e64 v231, 0, v231, s[48:49]
	ds_write_b32 v195, v230
	ds_write_b32 v79, v231
	v_pk_mul_f32 v[232:233], v[232:233], v[6:7] op_sel_hi:[1,0]
	s_nop 0
	v_pk_mul_f32 v[232:233], v[232:233], v[144:145]
	v_readlane_b32 s46, v255, 29
	v_readlane_b32 s47, v255, 30
	s_nop 1
	v_cndmask_b32_e64 v232, 0, v232, s[46:47]
	v_readlane_b32 s48, v255, 27
	v_readlane_b32 s49, v255, 28
	s_nop 1
	v_cndmask_b32_e64 v233, 0, v233, s[48:49]
	ds_write_b32 v196, v232
	ds_write_b32 v81, v233
	v_pk_mul_f32 v[234:235], v[234:235], v[6:7] op_sel:[0,1] op_sel_hi:[1,1]
	s_nop 0
	v_pk_mul_f32 v[234:235], v[234:235], v[146:147]
	v_readlane_b32 s46, v255, 33
	v_readlane_b32 s47, v255, 34
	s_nop 1
	v_cndmask_b32_e64 v234, 0, v234, s[46:47]
	v_readlane_b32 s48, v255, 31
	v_readlane_b32 s49, v255, 32
	s_nop 1
	v_cndmask_b32_e64 v235, 0, v235, s[48:49]
	ds_write_b32 v197, v234
	ds_write_b32 v83, v235
	v_pk_mul_f32 v[236:237], v[236:237], v[8:9] op_sel_hi:[1,0]
	s_nop 0
	v_pk_mul_f32 v[236:237], v[236:237], v[148:149]
	v_readlane_b32 s46, v255, 37
	v_readlane_b32 s47, v255, 38
	s_nop 1
	v_cndmask_b32_e64 v236, 0, v236, s[46:47]
	v_readlane_b32 s48, v255, 35
	v_readlane_b32 s49, v255, 36
	s_nop 1
	v_cndmask_b32_e64 v237, 0, v237, s[48:49]
	ds_write_b32 v198, v236
	ds_write_b32 v85, v237
	v_pk_mul_f32 v[238:239], v[238:239], v[8:9] op_sel:[0,1] op_sel_hi:[1,1]
	s_nop 0
	v_pk_mul_f32 v[238:239], v[238:239], v[150:151]
	v_readlane_b32 s46, v255, 41
	v_readlane_b32 s47, v255, 42
	s_nop 1
	v_cndmask_b32_e64 v238, 0, v238, s[46:47]
	v_readlane_b32 s48, v255, 39
	v_readlane_b32 s49, v255, 40
	s_nop 1
	v_cndmask_b32_e64 v239, 0, v239, s[48:49]
	ds_write_b32 v199, v238
	ds_write_b32 v87, v239
	v_pk_mul_f32 v[240:241], v[240:241], v[10:11] op_sel_hi:[1,0]
	s_nop 0
	v_pk_mul_f32 v[240:241], v[240:241], v[152:153]
	v_readlane_b32 s46, v255, 45
	v_readlane_b32 s47, v255, 46
	s_nop 1
	v_cndmask_b32_e64 v240, 0, v240, s[46:47]
	v_readlane_b32 s48, v255, 43
	v_readlane_b32 s49, v255, 44
	s_nop 1
	v_cndmask_b32_e64 v241, 0, v241, s[48:49]
	ds_write_b32 v200, v240
	ds_write_b32 v89, v241
	v_pk_mul_f32 v[242:243], v[242:243], v[10:11] op_sel:[0,1] op_sel_hi:[1,1]
	s_nop 0
	v_pk_mul_f32 v[242:243], v[242:243], v[154:155]
	s_nop 0
	v_cndmask_b32_e64 v242, 0, v242, s[76:77]
	v_cndmask_b32_e64 v243, 0, v243, s[74:75]
	ds_write_b32 v201, v242
	ds_write_b32 v91, v243
	v_pk_mul_f32 v[244:245], v[244:245], v[12:13] op_sel_hi:[1,0]
	s_nop 0
	v_pk_mul_f32 v[244:245], v[244:245], v[156:157]
	s_nop 0
	v_cndmask_b32_e64 v244, 0, v244, s[60:61]
	v_cndmask_b32_e64 v245, 0, v245, s[58:59]
	ds_write_b32 v202, v244
	ds_write_b32 v93, v245
	v_pk_mul_f32 v[248:249], v[248:249], v[12:13] op_sel:[0,1] op_sel_hi:[1,1]
	s_nop 0
	v_pk_mul_f32 v[248:249], v[248:249], v[158:159]
	s_nop 0
	v_cndmask_b32_e64 v248, 0, v248, s[64:65]
	v_cndmask_b32_e64 v249, 0, v249, s[62:63]
	ds_write_b32 v203, v248
	ds_write_b32 v95, v249
	v_pk_mul_f32 v[208:209], v[208:209], v[14:15] op_sel_hi:[1,0]
	s_nop 0
	v_pk_mul_f32 v[208:209], v[208:209], v[160:161]
	s_nop 0
	v_cndmask_b32_e64 v208, 0, v208, s[78:79]
	v_cndmask_b32_e64 v209, 0, v209, s[84:85]
	ds_write_b32 v204, v208
	ds_write_b32 v97, v209
	v_pk_mul_f32 v[210:211], v[210:211], v[14:15] op_sel:[0,1] op_sel_hi:[1,1]
	s_nop 0
	v_pk_mul_f32 v[210:211], v[210:211], v[162:163]
	s_nop 0
	v_cndmask_b32_e64 v210, 0, v210, s[26:27]
	v_cndmask_b32_e64 v211, 0, v211, s[80:81]
	ds_write_b32 v205, v210
	ds_write_b32 v99, v211
	v_pk_mul_f32 v[212:213], v[212:213], v[16:17] op_sel_hi:[1,0]
	s_nop 0
	v_pk_mul_f32 v[212:213], v[212:213], v[174:175]
	s_nop 0
	v_cndmask_b32_e64 v212, 0, v212, s[30:31]
	v_cndmask_b32_e64 v213, 0, v213, s[28:29]
	ds_write_b32 v206, v212
	ds_write_b32 v101, v213
	v_pk_mul_f32 v[214:215], v[214:215], v[16:17] op_sel:[0,1] op_sel_hi:[1,1]
	s_nop 0
	v_pk_mul_f32 v[214:215], v[214:215], v[176:177]
	s_nop 0
	v_cndmask_b32_e64 v214, 0, v214, s[36:37]
	v_cndmask_b32_e64 v215, 0, v215, s[24:25]
	ds_write_b32 v207, v214
	ds_write_b32 v103, v215
